# v18 + attention: one static s_setprio 1 for waves 4-7 during the query-subtile loops
# speedup vs baseline: 1.0074x; 1.0074x over previous
; #define LBAR() do { asm volatile("s_waitcnt lgkmcnt(0)" ::: "memory"); __builtin_amdgcn_s_barrier(); asm volatile("" ::: "memory"); } while (0)
; __device__ __forceinline__ void attn_unit(const AtArgs& A, unsigned char* lds, int unit, int tid, int wave, int lane) {
;     ...
;         if (valid) w = *(const u32x4*)(Q + t * QW + QC_V + kvh * 64 + c8 * 8);
;         const unsigned ww[4] = {w.x, w.y, w.z, w.w};
;         const int pkey = (((key >> 3) ^ c8) << 3) | (key & 7);
; #pragma unroll
;         for (int i = 0; i < 4; ++i) { VT[(c8 * 8 + 2 * i) * VST + pkey] = (bf16)(ww[i] & 0xffffu); VT[(c8 * 8 + 2 * i + 1) * VST + pkey] = (bf16)(ww[i] >> 16); }
;     }
;     *(u32x4*)(VT + (tid >> 3) * VST + (32 + (tid & 7)) * 8) = (u32x4){0u, 0u, 0u, 0u};
;     LBAR();
;     const int g = wave >> 1, qh = wave & 1, hq = kvh * 4 + g;
;     const float sink = A.sinks[hq];
; #pragma unroll 1
;     for (int st = 0; st < 4; ++st) {
.LBB0_509:
	s_or_b64 exec, exec, s[16:17]
	s_waitcnt vmcnt(0)
	ds_write_b16 v72, v0 offset:36864
	ds_write_b16_d16_hi v73, v0 offset:37552
	ds_write_b16 v72, v1 offset:38240
	ds_write_b16_d16_hi v73, v1 offset:38928
	ds_write_b16 v72, v2 offset:39616
	ds_write_b16_d16_hi v73, v2 offset:40304
	ds_write_b16 v72, v3 offset:40992
	ds_write_b16_d16_hi v73, v3 offset:41680
	ds_write_b128 v74, v[104:107] offset:37376
	s_lshl_b32 s6, s10, 2
	v_readlane_b32 s44, v242, 1
	s_waitcnt lgkmcnt(0)
	s_barrier
	v_mov_b32_e32 v0, s6
	v_readlane_b32 s54, v242, 11
	v_readlane_b32 s55, v242, 12
	s_lshr_b32 s6, s24, 5
	s_and_b32 s6, s6, 1
	s_lshl_b32 s6, s6, 8
	s_and_b32 s12, s35, 31
	s_add_i32 s6, s15, s6
	global_load_dword v38, v0, s[54:55]
	s_lshl_b32 s18, s12, 17
	s_lshl_b64 s[10:11], s[6:7], 1
	s_lshl_b32 s6, s12, 7
	s_cmp_lg_u32 s3, 0
	s_cselect_b64 s[16:17], -1, 0
	s_lshl_b64 s[12:13], s[20:21], 22
	s_or_b32 s3, s12, s18
	s_add_u32 s10, s3, s10
	s_addc_u32 s11, s13, s11
	s_add_u32 s0, s6, s0
	s_addc_u32 s1, 0, s1
	v_lshl_add_u64 v[0:1], s[0:1], 0, v[48:49]
	v_lshlrev_b64 v[0:1], 6, v[0:1]
	v_lshl_add_u64 v[52:53], v[46:47], 0, s[10:11]
	v_lshl_add_u64 v[54:55], s[8:9], 0, v[0:1]
	s_mov_b32 s3, 0xb000
	s_mov_b64 s[20:21], 0
	v_mov_b32_e32 v94, v87
	v_mov_b32_e32 v95, v86
	v_readlane_b32 s45, v242, 2
	v_readlane_b32 s46, v242, 3
	v_readlane_b32 s47, v242, 4
	v_readlane_b32 s48, v242, 5
	v_readlane_b32 s49, v242, 6
	v_readlane_b32 s50, v242, 7
	v_readlane_b32 s51, v242, 8
	v_readlane_b32 s52, v242, 9
	v_readlane_b32 s53, v242, 10
	v_readlane_b32 s56, v242, 13
	v_readlane_b32 s57, v242, 14
	v_readlane_b32 s58, v242, 15
	v_readlane_b32 s59, v242, 16
	v_readlane_b32 s98, v242, 17
	s_cmp_lt_u32 s98, 4
	s_cbranch_scc1 .Lattn_noprio
	s_setprio 1

; __device__ __forceinline__ void attn_unit(const AtArgs& A, unsigned char* lds, int unit, int tid, int wave, int lane) {
;     ...
;     }
; }
.LBB0_513:
	s_setprio 0
	s_mov_b64 s[0:1], 0
